# baseline (speedup 1.0000x reference)
; __device__ __forceinline__ int tid_() { int t = threadIdx.x; asm volatile("" : "+v"(t)); return t; }
; __device__ __forceinline__ void glax_item(char* shm, const Params& P, int l, int cgi, int hd, bf16x8 w2a0, bf16x8 w2a1,
;                                           float bias0, float bias1) {
;     ...
;   const int tid = tid_(), wid = tid >> 6, lane = tid & 63, fr = lane & 15, fq = lane >> 4;
;   const int dk = tid & 127, rg = tid >> 7;
;   const float qscale = 0.08838834764831845f;
;   const u16* hb = P.h + (long)(cgi * 64) * HS;
;   u16x8 qk[4];
; #pragma unroll
;   for (int k = 0; k < 2; ++k) {
;     const int u = tid + k * 512, row = u >> 4, c8 = (u & 15) * 8;
;     qk[k] = *(const u16x8*)(hb + (long)row * HS + C_Q + hd * 128 + c8);
;     qk[2 + k] = *(const u16x8*)(hb + (long)row * HS + C_K + hd * 128 + c8);
;   }
.LBB0_345:
	v_readfirstlane_b32 s8, v182
	s_lshr_b32 s8, s8, 8
	s_cmp_lg_u32 s8, 0
	s_cbranch_scc0 .Lmy_xprio
	s_setprio 1

; __device__ __forceinline__ int prow(int c) { return (c & ~31) | (((c >> 2) & 1) << 4) | (((c >> 3) & 3) << 2) | (c & 3); }
; __device__ __forceinline__ void glax_item(char* shm, const Params& P, int l, int cgi, int hd, bf16x8 w2a0, bf16x8 w2a1,
;                                           float bias0, float bias1) {
;     ...
;   if (tid < 256) *(u16x8*)(LR + (tid >> 2) * 32 + (tid & 3) * 8) = *(const u16x8*)(hb + (long)(tid >> 2) * HS + C_LRF + (tid & 3) * 8);
; #pragma unroll
;   for (int k = 0; k < 4; ++k) {
;     int u = tid + k * 512, j = u >> 5, c8 = (u & 31) * 8;
;     u16x8 v = *(const u16x8*)(hb + (long)j * HS + C_V + hd * 256 + c8);
; #pragma unroll
;     for (int e = 0; e < 8; ++e) VT[prow(c8 + e) * JP + j] = v[e];
;   }
;   __syncthreads();
;   u16 qraw[16], kraw[16];
; #pragma unroll
;   for (int rr = 0; rr < 16; ++rr) {
;     qraw[rr] = Q[(rg * 16 + rr) * 128 + dk];
;     kraw[rr] = Q[64 * 128 + (rg * 16 + rr) * 128 + dk];
;   }
;   {
;     u16* vtg = P.vtg + (long)(cgi * 4 + hd) * 256 * 64;
; #pragma unroll
;     for (int k = 0; k < 4; ++k) {
;       int u = tid + k * 512, dv = u >> 3, j8 = (u & 7) * 8;
;       *(u16x8*)(vtg + dv * 64 + j8) = *(const u16x8*)(VT + prow(dv) * JP + j8);
;     }
.LBB0_347:
	s_or_b64 exec, exec, s[8:9]
	v_ashrrev_i32_e32 v18, 5, v24
	v_mov_b64_e32 v[14:15], s[6:7]
	v_and_b32_e32 v12, 0xf8, v22
	v_mad_i64_i32 v[10:11], s[6:7], v18, s66, v[14:15]
	s_lshl_b32 s58, s67, 9
	v_lshrrev_b32_e32 v13, 1, v22
	v_lshl_add_u64 v[10:11], v[10:11], 0, s[58:59]
	v_lshlrev_b32_e32 v30, 1, v12
	v_mov_b32_e32 v31, v1
	v_and_b32_e32 v12, 0xe0, v22
	v_lshl_add_u64 v[10:11], v[10:11], 0, v[30:31]
	v_and_or_b32 v12, v13, 12, v12
	v_mul_u32_u24_e32 v20, 0x90, v12
	v_bfe_u32 v216, v24, 2, 3
	v_bfe_u32 v217, v24, 5, 3
	v_lshl_add_u32 v217, v217, 1, v20
	v_lshrrev_b32_e32 v219, 8, v24
	v_xor_b32_e32 v220, v219, v216
	v_lshl_add_u32 v18, v220, 4, v217
	v_add_u32_e32 v70, 0x400, v24
	v_add_u32_e32 v74, 0x600, v24
	s_ashr_i32 s97, s96, 31
	v_readlane_b32 s8, v248, 3
	v_and_b32_e32 v16, 0x7f, v24
	v_readlane_b32 s9, v248, 4
	v_ashrrev_i32_e32 v26, 7, v24
	v_bfe_u32 v28, v24, 4, 2
	v_and_b32_e32 v23, 15, v24
	ds_write_b16 v18, v196 offset:34816
	ds_write_b16_d16_hi v18, v196 offset:34960
	ds_write_b16 v18, v197 offset:35104
	ds_write_b16_d16_hi v18, v197 offset:35248
	ds_write_b16 v18, v198 offset:37120
	ds_write_b16_d16_hi v18, v198 offset:37264
	ds_write_b16 v18, v199 offset:37408
	ds_write_b16_d16_hi v18, v199 offset:37552
	v_ashrrev_i32_e32 v12, 5, v21
	v_mad_i64_i32 v[10:11], s[6:7], v12, s66, v[14:15]
	v_lshl_add_u64 v[10:11], v[10:11], 0, s[58:59]
	v_lshl_add_u64 v[10:11], v[10:11], 0, v[30:31]
	v_or_b32_e32 v220, 2, v219
	v_xor_b32_e32 v220, v220, v216
	v_lshl_add_u32 v18, v220, 4, v217
	ds_write_b16 v18, v200 offset:34816
	ds_write_b16_d16_hi v18, v200 offset:34960
	ds_write_b16 v18, v201 offset:35104
	ds_write_b16_d16_hi v18, v201 offset:35248
	ds_write_b16 v18, v202 offset:37120
	ds_write_b16_d16_hi v18, v202 offset:37264
	ds_write_b16 v18, v203 offset:37408
	ds_write_b16_d16_hi v18, v203 offset:37552
	v_ashrrev_i32_e32 v12, 5, v70
	v_mad_i64_i32 v[10:11], s[6:7], v12, s66, v[14:15]
	v_lshl_add_u64 v[10:11], v[10:11], 0, s[58:59]
	v_lshl_add_u64 v[10:11], v[10:11], 0, v[30:31]
	v_or_b32_e32 v220, 4, v219
	v_xor_b32_e32 v220, v220, v216
	v_lshl_add_u32 v18, v220, 4, v217
	ds_write_b16 v18, v204 offset:34816
	ds_write_b16_d16_hi v18, v204 offset:34960
	ds_write_b16 v18, v205 offset:35104
	ds_write_b16_d16_hi v18, v205 offset:35248
	ds_write_b16 v18, v206 offset:37120
	ds_write_b16_d16_hi v18, v206 offset:37264
	ds_write_b16 v18, v207 offset:37408
	ds_write_b16_d16_hi v18, v207 offset:37552
	v_ashrrev_i32_e32 v12, 5, v74
	v_mad_i64_i32 v[10:11], s[6:7], v12, s66, v[14:15]
	v_lshl_add_u64 v[10:11], v[10:11], 0, s[58:59]
	v_lshl_add_u64 v[10:11], v[10:11], 0, v[30:31]
	v_or_b32_e32 v220, 6, v219
	v_xor_b32_e32 v220, v220, v216
	v_lshl_add_u32 v14, v220, 4, v217
	s_lshl_b64 s[6:7], s[96:97], 15
	s_add_u32 s6, s8, s6
	v_lshlrev_b32_e32 v18, 1, v16
	s_addc_u32 s7, s9, s7
	v_mov_b32_e32 v15, v1
	v_lshlrev_b32_e32 v20, 4, v28
	ds_write_b16 v14, v208 offset:34816
	ds_write_b16_d16_hi v14, v208 offset:34960
	ds_write_b16 v14, v209 offset:35104
	ds_write_b16_d16_hi v14, v209 offset:35248
	ds_write_b16 v14, v210 offset:37120
	ds_write_b16_d16_hi v14, v210 offset:37264
	ds_write_b16 v14, v211 offset:37408
	ds_write_b16_d16_hi v14, v211 offset:37552
	v_and_b32_e32 v14, 0x70, v27
	v_lshl_or_b32 v10, v26, 12, v18
	v_lshl_add_u64 v[66:67], s[6:7], 0, v[14:15]
	v_ashrrev_i32_e32 v15, 3, v24
	s_waitcnt lgkmcnt(0)
	s_barrier
	ds_read_u16 v73, v10
	ds_read_u16 v57, v10 offset:16384
	ds_read_u16 v71, v10 offset:256
	ds_read_u16 v72, v10 offset:16640
	ds_read_u16 v56, v10 offset:512
	ds_read_u16 v53, v10 offset:16896
	ds_read_u16 v54, v10 offset:768
	ds_read_u16 v55, v10 offset:17152
	ds_read_u16 v52, v10 offset:1024
	ds_read_u16 v49, v10 offset:17408
	ds_read_u16 v50, v10 offset:1280
	ds_read_u16 v51, v10 offset:17664
	ds_read_u16 v48, v10 offset:1536
	ds_read_u16 v45, v10 offset:17920
	ds_read_u16 v46, v10 offset:1792
	ds_read_u16 v47, v10 offset:18176
	ds_read_u16 v44, v10 offset:2048
	ds_read_u16 v41, v10 offset:18432
	ds_read_u16 v42, v10 offset:2304
	ds_read_u16 v43, v10 offset:18688
	ds_read_u16 v40, v10 offset:2560
	ds_read_u16 v37, v10 offset:18944
	ds_read_u16 v38, v10 offset:2816
	ds_read_u16 v39, v10 offset:19200
	ds_read_u16 v36, v10 offset:3072
	ds_read_u16 v33, v10 offset:19456
	ds_read_u16 v34, v10 offset:3328
	ds_read_u16 v35, v10 offset:19712
	ds_read_u16 v32, v10 offset:3584
	ds_read_u16 v29, v10 offset:19968
	ds_read_u16 v30, v10 offset:3840
	ds_read_u16 v31, v10 offset:20224
	v_lshlrev_b32_e32 v10, 2, v15
	v_lshrrev_b32_e32 v11, 1, v15
	v_and_b32_e32 v10, 16, v10
	v_and_b32_e32 v11, 12, v11
	v_and_b32_e32 v12, 0xfffffe3, v15
	v_or3_b32 v10, v12, v10, v11
	v_bfe_u32 v216, v15, 5, 3
	v_lshlrev_b32_e32 v216, 4, v216
	v_xor_b32_e32 v216, v216, v14
	v_mad_u64_u32 v[10:11], s[6:7], v10, s84, v[216:217]
	ds_read_b128 v[10:13], v10 offset:34816
	v_lshlrev_b32_e32 v68, 6, v15
	v_ashrrev_i32_e32 v69, 31, v68
	v_lshl_add_u64 v[68:69], v[68:69], 1, v[66:67]
	v_ashrrev_i32_e32 v15, 3, v21
	s_waitcnt lgkmcnt(0)
	global_store_dwordx4 v[68:69], v[10:13], off
	v_lshlrev_b32_e32 v68, 6, v15
	v_ashrrev_i32_e32 v69, 31, v68
	v_lshlrev_b32_e32 v10, 2, v15
	v_lshrrev_b32_e32 v11, 1, v15
	v_and_b32_e32 v10, 16, v10
	v_and_b32_e32 v11, 12, v11
	v_and_b32_e32 v12, 0xfffffe3, v15
	v_or3_b32 v10, v12, v10, v11
	v_bfe_u32 v216, v15, 5, 3
	v_lshlrev_b32_e32 v216, 4, v216
	v_xor_b32_e32 v216, v216, v14
	v_mad_u64_u32 v[10:11], s[6:7], v10, s84, v[216:217]
	ds_read_b128 v[10:13], v10 offset:34816
	v_lshl_add_u64 v[68:69], v[68:69], 1, v[66:67]
	v_ashrrev_i32_e32 v15, 3, v70
	s_waitcnt lgkmcnt(0)
; __device__ __forceinline__ void glax_z(float* Z, const u16* LR, int dir, bf16x8 w2a, int wid, int fr, int fq) {
; #pragma unroll
;   for (int rt = 0; rt < 4; ++rt) {
;     bf16x8 b = bf16x8{0, 0, 0, 0, 0, 0, 0, 0};
;     if (fq < 2) b = *(const bf16x8*)(LR + (rt * 16 + fr) * 32 + dir * 16 + fq * 8);
;     f32x4 d = __builtin_amdgcn_mfma_f32_16x16x32_bf16(w2a, b, f32x4{0.f, 0.f, 0.f, 0.f}, 0, 0, 0);
;     *(f32x4*)(Z + (rt * 16 + fr) * ZP + wid * 16 + fq * 4) = d;
;   }
; __device__ __forceinline__ void glax_item(char* shm, const Params& P, int l, int cgi, int hd, bf16x8 w2a0, bf16x8 w2a1,
;                                           float bias0, float bias1) {
;     ...
;     u16* vtg = P.vtg + (long)(cgi * 4 + hd) * 256 * 64;
; #pragma unroll
;     for (int k = 0; k < 4; ++k) {
;       int u = tid + k * 512, dv = u >> 3, j8 = (u & 7) * 8;
;       *(u16x8*)(vtg + dv * 64 + j8) = *(const u16x8*)(VT + prow(dv) * JP + j8);
;     }
;   }
;   glax_z(Z, LR, 0, w2a0, wid, fr, fq);
;   __syncthreads();
;   f32x4 osum[4][2];
; #pragma unroll
;   for (int it = 0; it < 4; ++it)
; #pragma unroll
;     for (int d = 0; d < 2; ++d) osum[it][d] = f32x4{0.f, 0.f, 0.f, 0.f};
; #pragma unroll 1
;   for (int dir = 0; dir < 2; ++dir) {
;     char* img = P.img + ((long)(dir * NCH + cgi) * 4 + hd) * IMG_B;
;     u16* o = P.of;
;     const float bias = dir ? bias1 : bias0;
;     float g[16];
; #pragma unroll
;     for (int rr = 0; rr < 16; ++rr) {
;       const float z = Z[(rg * 16 + rr) * ZP + dk] + bias;
;       g[rr] = (fminf(z, 0.f) - __builtin_amdgcn_logf(1.0f + __expf(-fabsf(z))) * 0.69314718f) * (1.0f / 16.0f);
;     }
;     if (!dir) {
; #pragma unroll
;       for (int rr = 1; rr < 16; ++rr) g[rr] += g[rr - 1];
;       GT[rg * 128 + dk] = g[15];
;     } else {
; #pragma unroll
;     ...
;       GT[rg * 128 + dk] = g[0];
;     }
;     __syncthreads();
;     {
;       float gt0 = GT[dk], gt1 = GT[128 + dk], gt2 = GT[256 + dk], gt3 = GT[384 + dk];
;       float blast = gt0 + gt1 + gt2 + gt3;
;       float off;
;       if (!dir) off = (rg > 0 ? gt0 : 0.f) + (rg > 1 ? gt1 : 0.f) + (rg > 2 ? gt2 : 0.f);
;       else off = (rg < 3 ? gt3 : 0.f) + (rg < 2 ? gt2 : 0.f) + (rg < 1 ? gt1 : 0.f);
;       if (dir == 0) glax_z(Z, LR, 1, w2a1, wid, fr, fq);
;       const float eblast = __expf(blast);
;       u16x8 kd0, kd1;
; #pragma unroll
;       for (int rr = 0; rr < 16; ++rr) {
	global_store_dwordx4 v[68:69], v[10:13], off
	s_nop 1
	v_lshlrev_b32_e32 v10, 2, v15
	v_lshrrev_b32_e32 v11, 1, v15
	v_and_b32_e32 v10, 16, v10
	v_and_b32_e32 v11, 12, v11
	v_and_b32_e32 v12, 0xfffffe3, v15
	v_or3_b32 v10, v12, v10, v11
	v_bfe_u32 v216, v15, 5, 3
	v_lshlrev_b32_e32 v216, 4, v216
	v_xor_b32_e32 v216, v216, v14
	v_mad_u64_u32 v[10:11], s[6:7], v10, s84, v[216:217]
	ds_read_b128 v[10:13], v10 offset:34816
	v_lshlrev_b32_e32 v68, 6, v15
	v_ashrrev_i32_e32 v69, 31, v68
	v_lshl_add_u64 v[68:69], v[68:69], 1, v[66:67]
	v_ashrrev_i32_e32 v15, 3, v74
	s_waitcnt lgkmcnt(0)
	global_store_dwordx4 v[68:69], v[10:13], off
	s_nop 1
	v_lshlrev_b32_e32 v10, 2, v15
	v_lshrrev_b32_e32 v11, 1, v15
	v_and_b32_e32 v10, 16, v10
	v_and_b32_e32 v11, 12, v11
	v_and_b32_e32 v12, 0xfffffe3, v15
	v_or3_b32 v10, v12, v10, v11
	v_bfe_u32 v216, v15, 5, 3
	v_lshlrev_b32_e32 v216, 4, v216
	v_xor_b32_e32 v216, v216, v14
	v_mad_u64_u32 v[10:11], s[6:7], v10, s84, v[216:217]
	ds_read_b128 v[10:13], v10 offset:34816
	v_lshlrev_b32_e32 v14, 6, v15
	v_ashrrev_i32_e32 v15, 31, v14
	v_lshl_add_u64 v[14:15], v[14:15], 1, v[66:67]
	v_cmp_gt_u32_e64 s[6:7], 2, v28
	s_waitcnt lgkmcnt(0)
	global_store_dwordx4 v[14:15], v[10:13], off
	v_mov_b32_e32 v14, 0
	v_mov_b32_e32 v15, 0
	v_lshl_or_b32 v11, v23, 6, v194
	v_mov_b32_e32 v10, 0
	v_add_u32_e32 v105, v11, v20
	v_mov_b32_e32 v12, 0
	v_mov_b32_e32 v13, 0
	s_and_saveexec_b64 s[8:9], s[6:7]
	ds_read_b128 v[12:15], v105
	s_or_b64 exec, exec, s[8:9]
	s_movk_i32 s8, 0xffc0
	s_waitcnt lgkmcnt(0)
	v_mfma_f32_16x16x32_bf16 v[12:15], v[2:5], v[12:15], 0
	v_and_or_b32 v11, v24, s8, v20
	v_add_u32_e32 v66, 0x15400, v11
	s_movk_i32 s8, 0x210
	v_mad_u32_u24 v11, v23, s8, v66
	s_nop 3
	ds_write_b128 v11, v[12:15]
	v_mov_b32_e32 v11, 0
	v_mov_b32_e32 v12, 0
	v_mov_b32_e32 v13, 0
	s_and_saveexec_b64 s[8:9], s[6:7]
	ds_read_b128 v[10:13], v105 offset:1024
	s_or_b64 exec, exec, s[8:9]
	s_waitcnt lgkmcnt(0)
	v_mfma_f32_16x16x32_bf16 v[10:13], v[2:5], v[10:13], 0
	v_mul_u32_u24_e32 v14, 0x210, v23
	v_add_u32_e32 v106, v66, v14
	v_mov_b32_e32 v14, 0
	v_mov_b32_e32 v15, 0
	s_nop 3
	ds_write_b128 v106, v[10:13] offset:8448
	v_mov_b32_e32 v10, 0
	v_mov_b32_e32 v12, 0
	v_mov_b32_e32 v13, 0
	s_and_saveexec_b64 s[8:9], s[6:7]
	ds_read_b128 v[12:15], v105 offset:2048
	s_or_b64 exec, exec, s[8:9]
	s_waitcnt lgkmcnt(0)
	v_mfma_f32_16x16x32_bf16 v[12:15], v[2:5], v[12:15], 0
	s_lshl_b32 s56, s67, 8
	v_mov_b32_e32 v11, 0
	s_nop 5
	ds_write_b128 v106, v[12:15] offset:16896
	v_mov_b32_e32 v12, 0
	v_mov_b32_e32 v13, 0
	s_and_saveexec_b64 s[8:9], s[6:7]
	ds_read_b128 v[10:13], v105 offset:3072
	s_or_b64 exec, exec, s[8:9]
	s_waitcnt lgkmcnt(0)
	v_mfma_f32_16x16x32_bf16 v[10:13], v[2:5], v[10:13], 0
	v_lshlrev_b32_e32 v15, 6, v16
	v_and_b32_e32 v15, 0x3c0, v15
	v_lshlrev_b32_e32 v66, 5, v26
	v_and_or_b32 v15, v66, 32, v15
	v_ashrrev_i32_e32 v14, 6, v24
	s_nop 2
	ds_write_b128 v106, v[10:13] offset:25344
	v_lshrrev_b32_e32 v11, 3, v24
	v_lshlrev_b32_e32 v10, 2, v16
	v_and_b32_e32 v11, 14, v11
	v_lshrrev_b32_e32 v13, 8, v24
	v_lshlrev_b32_e32 v12, 4, v26
	v_or_b32_e32 v102, 0x15400, v10
	v_or_b32_e32 v107, 0x14c00, v10
	v_add_lshl_u32 v11, v11, v13, 10
	v_and_b32_e32 v10, 32, v10
	v_or_b32_e32 v13, 16, v15
	s_movk_i32 s8, 0x80
	s_movk_i32 s22, 0x2100
	v_bitop3_b32 v66, v15, v11, v10 bitop3:0xde
	v_bitop3_b32 v68, v13, v11, v10 bitop3:0xde
	v_cmp_gt_u32_e64 s[8:9], s8, v24
	v_and_b32_e32 v13, 0xc0, v27
	v_lshlrev_b32_e32 v10, 1, v14
	v_or_b32_e32 v27, v12, v23
	v_lshl_add_u32 v108, v24, 2, v195
	v_mul_lo_u32 v24, v26, s22
	v_or_b32_e32 v12, 1, v12
	s_movk_i32 s22, 0x210
	v_lshrrev_b32_e32 v15, 5, v25
	v_and_b32_e32 v25, 2, v10
	v_mul_lo_u32 v10, v27, s84
	v_lshlrev_b32_e32 v11, 3, v28
	s_mov_b32 s11, 0x11800
	v_mul_lo_u32 v141, v12, s22
	s_movk_i32 s22, 0x880
	v_lshlrev_b32_e32 v94, 2, v28
	v_add3_u32 v28, v10, v11, s11
	v_or_b32_e32 v70, s10, v23
	v_cmp_gt_i32_e64 s[10:11], 3, v26
	v_cmp_gt_i32_e64 s[12:13], 2, v26
	v_cmp_gt_i32_e64 s[14:15], 1, v26
	v_cmp_lt_i32_e64 s[16:17], 0, v26
	v_cmp_lt_i32_e64 s[18:19], 1, v26
	v_cmp_lt_i32_e64 s[20:21], 2, v26
	v_mul_lo_u32 v26, v26, s22
	v_mad_u64_u32 v[74:75], s[22:23], v12, s85, v[18:19]
	v_lshlrev_b32_e32 v12, 16, v56
	v_mul_f32_e32 v75, 0x3db504f3, v12
	v_lshlrev_b32_e32 v12, 16, v54
	v_mul_f32_e32 v113, 0x3db504f3, v12
	v_lshlrev_b32_e32 v12, 16, v52
	v_mul_f32_e32 v115, 0x3db504f3, v12
	v_lshlrev_b32_e32 v12, 16, v50
	v_mul_f32_e32 v117, 0x3db504f3, v12
	v_lshlrev_b32_e32 v12, 16, v48
	v_mul_f32_e32 v119, 0x3db504f3, v12
	v_lshlrev_b32_e32 v12, 16, v46
	v_mul_f32_e32 v121, 0x3db504f3, v12
	v_lshlrev_b32_e32 v12, 16, v44
	v_mul_f32_e32 v123, 0x3db504f3, v12
	v_lshlrev_b32_e32 v12, 16, v42
	v_mul_f32_e32 v125, 0x3db504f3, v12
	v_lshlrev_b32_e32 v12, 16, v40
	v_mul_f32_e32 v127, 0x3db504f3, v12
	v_lshlrev_b32_e32 v12, 16, v38
	v_mul_f32_e32 v129, 0x3db504f3, v12
	v_lshlrev_b32_e32 v12, 16, v36
	v_mul_f32_e32 v131, 0x3db504f3, v12
	v_lshlrev_b32_e32 v12, 16, v34
	v_mul_f32_e32 v133, 0x3db504f3, v12
	v_lshlrev_b32_e32 v12, 16, v32
	v_mul_f32_e32 v135, 0x3db504f3, v12
	v_lshlrev_b32_e32 v12, 16, v30
	v_mul_f32_e32 v137, 0x3db504f3, v12
	v_mul_lo_u32 v12, v19, s85
	v_and_b32_e32 v18, 24, v22
	s_mov_b32 s23, 0x3ffffc
	v_and_b32_e32 v0, 48, v0
	v_lshlrev_b32_e32 v10, 5, v14
	v_add3_u32 v139, v13, v12, v18
	v_and_or_b32 v12, v14, s23, v15
	v_lshlrev_b32_e32 v14, 6, v19
	s_movk_i32 s22, 0x3c0
	v_lshlrev_b32_e32 v19, 2, v19
	v_and_or_b32 v14, v14, s22, v0
	v_lshlrev_b32_e32 v12, 10, v12
	v_and_b32_e32 v19, 32, v19
	v_bitop3_b32 v90, v14, v12, v19 bitop3:0xde
	v_mul_lo_u32 v12, v17, s85
; __device__ __forceinline__ int prow(int c) { return (c & ~31) | (((c >> 2) & 1) << 4) | (((c >> 3) & 3) << 2) | (c & 3); }
; __device__ __forceinline__ void glax_item(char* shm, const Params& P, int l, int cgi, int hd, bf16x8 w2a0, bf16x8 w2a1,
;                                           float bias0, float bias1) {
;     ...
;   u16 qraw[16], kraw[16];
; #pragma unroll
;   for (int rr = 0; rr < 16; ++rr) {
;     qraw[rr] = Q[(rg * 16 + rr) * 128 + dk];
;     kraw[rr] = Q[64 * 128 + (rg * 16 + rr) * 128 + dk];
;   }
;   {
;     u16* vtg = P.vtg + (long)(cgi * 4 + hd) * 256 * 64;
; #pragma unroll
;     for (int k = 0; k < 4; ++k) {
;       int u = tid + k * 512, dv = u >> 3, j8 = (u & 7) * 8;
;       *(u16x8*)(vtg + dv * 64 + j8) = *(const u16x8*)(VT + prow(dv) * JP + j8);
;     }
;   }
;   glax_z(Z, LR, 0, w2a0, wid, fr, fq);
;   __syncthreads();
;   f32x4 osum[4][2];
; #pragma unroll
;   for (int it = 0; it < 4; ++it)
; #pragma unroll
;     for (int d = 0; d < 2; ++d) osum[it][d] = f32x4{0.f, 0.f, 0.f, 0.f};
;     ...
;       const int ti = wid >> 1, tj0 = (wid & 1) * 2;
;       bf16x8 qf[4];
; #pragma unroll
;       for (int ks = 0; ks < 4; ++ks) qf[ks] = *(const bf16x8*)(Q + (ti * 16 + fr) * QP + ks * 32 + fq * 8);
; #pragma unroll
;       for (int jj = 0; jj < 2; ++jj) {
;         f32x4 sc = f32x4{0.f, 0.f, 0.f, 0.f};
; #pragma unroll
;         for (int ks = 0; ks < 4; ++ks) {
;           bf16x8 kf = *(const bf16x8*)(Kt + ((tj0 + jj) * 16 + fr) * QP + ks * 32 + fq * 8);
;           sc = __builtin_amdgcn_mfma_f32_16x16x32_bf16(kf, qf[ks], sc, 0, 0, 0);
;         }
;         const int i = ti * 16 + fr;
;         u16x4 pv;
; #pragma unroll
;         for (int e = 0; e < 4; ++e) {
;           int j = (tj0 + jj) * 16 + fq * 4 + e;
;           bool keep = dir ? (j >= i) : (j <= i);
;           pv[e] = keep ? f2bf(sc[e]) : (u16)0;
;         }
;         *(u16x4*)(Pm + i * JP + (tj0 + jj) * 16 + fq * 4) = pv;
	v_add3_u32 v140, v13, v12, v18
	v_lshrrev_b32_e32 v12, 6, v21
	v_lshlrev_b32_e32 v13, 6, v17
	v_and_or_b32 v12, v12, s23, v15
	v_and_or_b32 v0, v13, s22, v0
	v_lshlrev_b32_e32 v13, 2, v17
	v_lshlrev_b32_e32 v12, 10, v12
	v_and_b32_e32 v13, 32, v13
	v_bitop3_b32 v92, v0, v12, v13 bitop3:0xde
	v_lshlrev_b32_e32 v0, 4, v25
	v_or_b32_e32 v12, v0, v23
	v_or_b32_e32 v0, v0, v94
	v_mul_u32_u24_e32 v17, 0x110, v12
	v_or_b32_e32 v12, 1, v0
	v_cmp_ge_i32_e64 s[22:23], v0, v27
	v_cmp_le_i32_e64 s[24:25], v0, v27
	v_cmp_ge_i32_e64 s[26:27], v12, v27
	v_cmp_lt_i32_e64 s[28:29], v0, v27
	v_or_b32_e32 v12, 2, v0
	v_or_b32_e32 v0, 3, v0
	v_cmp_ge_i32_e64 s[36:37], v0, v27
	v_cmp_le_i32_e64 s[38:39], v0, v27
	v_or_b32_e32 v0, 1, v25
	v_cmp_ge_i32_e64 s[30:31], v12, v27
	v_cmp_le_i32_e64 s[34:35], v12, v27
	v_lshlrev_b32_e32 v12, 4, v0
	s_lshl_b32 s56, s56, 1
	v_readlane_b32 s60, v248, 0
	v_or_b32_e32 v13, v12, v23
	v_or_b32_e32 v12, v12, v94
	v_readlane_b32 s61, v248, 1
	s_add_u32 s56, s60, s56
	v_ashrrev_i32_e32 v11, 31, v10
	v_or_b32_e32 v26, v26, v16
	v_lshlrev_b32_e32 v22, 5, v25
	v_mul_u32_u24_e32 v25, 0x110, v13
	v_or_b32_e32 v13, 1, v12
	v_or_b32_e32 v14, 16, v70
	v_or_b32_e32 v18, 32, v70
	s_addc_u32 s57, s61, 0
	v_or_b32_e32 v95, v10, v23
	v_lshlrev_b32_e32 v110, 1, v26
	v_lshlrev_b32_e32 v26, 16, v71
	v_cmp_ge_i32_e64 s[40:41], v12, v27
	v_cmp_le_i32_e64 s[42:43], v12, v27
	v_cmp_ge_i32_e64 s[44:45], v13, v27
	v_cmp_lt_i32_e64 s[46:47], v12, v27
	v_or_b32_e32 v13, 2, v12
	v_or_b32_e32 v12, 3, v12
	v_ashrrev_i32_e32 v71, 31, v70
	v_ashrrev_i32_e32 v15, 31, v14
	v_ashrrev_i32_e32 v19, 31, v18
	v_lshl_add_u64 v[10:11], v[10:11], 1, s[56:57]
	v_mov_b32_e32 v21, v1
	v_mul_lo_u32 v103, v27, s85
	v_or_b32_e32 v148, 0x11800, v20
	v_lshlrev_b32_e32 v73, 16, v73
	v_mul_f32_e32 v111, 0x3db504f3, v26
	v_cmp_ge_i32_e64 s[48:49], v13, v27
	v_cmp_le_i32_e64 s[50:51], v13, v27
	v_cmp_ge_i32_e64 s[52:53], v12, v27
	v_cmp_le_i32_e64 s[54:55], v12, v27
	v_lshlrev_b32_e32 v26, 5, v0
	v_mul_lo_u32 v27, v95, s84
	v_mul_u32_u24_e32 v23, 0x90, v23
	v_lshlrev_b64 v[12:13], 11, v[70:71]
	v_lshlrev_b64 v[14:15], 11, v[14:15]
	v_lshlrev_b64 v[18:19], 11, v[18:19]
	v_lshl_add_u64 v[94:95], v[10:11], 0, v[20:21]
	v_mov_b32_e32 v10, 0
	s_mov_b32 s58, 0
	v_ashrrev_i32_e32 v67, 31, v66
	v_ashrrev_i32_e32 v69, 31, v68
	v_mul_f32_e32 v109, 0x3db504f3, v73
	v_lshlrev_b32_e32 v73, 16, v72
	v_lshlrev_b32_e32 v72, 16, v57
	v_add_u32_e32 v112, 0x110, v74
	v_lshlrev_b32_e32 v77, 16, v55
	v_lshlrev_b32_e32 v76, 16, v53
	v_add_u32_e32 v114, 0x220, v74
	v_add_u32_e32 v116, 0x330, v74
	v_lshlrev_b32_e32 v79, 16, v51
	v_lshlrev_b32_e32 v78, 16, v49
	v_add_u32_e32 v118, 0x440, v74
	v_add_u32_e32 v120, 0x550, v74
	v_lshlrev_b32_e32 v81, 16, v47
	v_lshlrev_b32_e32 v80, 16, v45
	v_add_u32_e32 v122, 0x660, v74
	v_add_u32_e32 v124, 0x770, v74
	v_lshlrev_b32_e32 v83, 16, v43
	v_lshlrev_b32_e32 v82, 16, v41
	v_add_u32_e32 v126, 0x880, v74
	v_add_u32_e32 v128, 0x990, v74
	v_lshlrev_b32_e32 v85, 16, v39
	v_lshlrev_b32_e32 v84, 16, v37
	v_add_u32_e32 v130, 0xaa0, v74
	v_add_u32_e32 v132, 0xbb0, v74
	v_lshlrev_b32_e32 v87, 16, v35
	v_lshlrev_b32_e32 v86, 16, v33
	v_add_u32_e32 v134, 0xcc0, v74
	v_add_u32_e32 v136, 0xdd0, v74
	v_lshlrev_b32_e32 v89, 16, v31
	v_lshlrev_b32_e32 v88, 16, v29
	v_add_u32_e32 v138, 0xee0, v74
	v_ashrrev_i32_e32 v91, 31, v90
	v_ashrrev_i32_e32 v93, 31, v92
	v_lshl_add_u64 v[96:97], v[94:95], 0, v[12:13]
	v_lshl_add_u64 v[98:99], v[94:95], 0, v[14:15]
	v_lshl_add_u64 v[100:101], v[94:95], 0, v[18:19]
	s_mov_b64 s[84:85], -1
	v_add_u32_e32 v71, v102, v24
	v_add_u32_e32 v141, v102, v141
	v_lshlrev_b32_e32 v0, 2, v16
	v_add_u32_e32 v142, v103, v20
	v_add_u32_e32 v143, v20, v17
	v_add_u32_e32 v144, v28, v22
	v_add_u32_e32 v145, v20, v25
	v_add_u32_e32 v146, v28, v26
	v_lshrrev_b32_e32 v216, 4, v182
	v_lshrrev_b32_e32 v217, 6, v182
	v_xor_b32_e32 v216, v216, v217
	v_and_b32_e32 v216, 3, v216
	v_bfe_u32 v217, v182, 8, 1
	v_lshl_add_u32 v216, v217, 2, v216
	v_lshl_add_u32 v147, v216, 4, v27
	v_xor_b32_e32 v216, 4, v216
	v_lshl_add_u32 v218, v216, 4, v27
	v_add_u32_e32 v148, v148, v23
	v_mov_b32_e32 v11, v10
	v_mov_b32_e32 v12, v10
	v_mov_b32_e32 v13, v10
	v_mov_b32_e32 v14, v10
	v_mov_b32_e32 v15, v10
	v_mov_b32_e32 v16, v10
	v_mov_b32_e32 v17, v10
	v_mov_b32_e32 v18, v10
	v_mov_b32_e32 v19, v10
	v_mov_b32_e32 v20, v10
	v_mov_b32_e32 v21, v10
	v_mov_b32_e32 v22, v10
	v_mov_b32_e32 v23, v10
	v_mov_b32_e32 v24, v10
	v_mov_b32_e32 v25, v10
	v_mov_b32_e32 v26, v10
	v_mov_b32_e32 v27, v10
	v_mov_b32_e32 v28, v10
	v_mov_b32_e32 v29, v10
	v_mov_b32_e32 v34, v10
	v_mov_b32_e32 v35, v10
	v_mov_b32_e32 v36, v10
	v_mov_b32_e32 v37, v10
	v_mov_b32_e32 v30, v10
	v_mov_b32_e32 v31, v10
	v_mov_b32_e32 v32, v10
	v_mov_b32_e32 v33, v10
	v_mov_b32_e32 v38, v10
	v_mov_b32_e32 v39, v10
	v_mov_b32_e32 v40, v10
	v_mov_b32_e32 v41, v10
	s_waitcnt lgkmcnt(0)
	s_barrier
	s_branch .LBB0_357
	s_nop 0
	s_nop 0
	s_nop 0
	s_nop 0
	s_nop 0
	s_nop 0
	s_nop 0
	s_nop 0
	s_nop 0
	s_nop 0
	s_nop 0
	s_nop 0
	s_nop 0
	s_nop 0
	s_nop 0
	s_nop 0
	s_nop 0
	s_nop 0
	s_nop 0
	s_nop 0
	s_nop 0
	s_nop 0
	s_nop 0
	s_nop 0
	s_nop 0
	s_nop 0
	s_nop 0
	s_nop 0
	s_nop 0
	s_nop 0
	s_nop 0
	s_nop 0
	s_nop 0
	s_nop 0
	s_nop 0
	s_nop 0
	s_nop 0
	s_nop 0
	s_nop 0
	s_nop 0
	s_nop 0
	s_nop 0
	s_nop 0
	s_nop 0
	s_nop 0
	s_nop 0
	s_nop 0
	s_nop 0
	s_nop 0
	s_nop 0
	s_nop 0
	s_nop 0
	s_nop 0
	s_nop 0
	s_nop 0
	s_nop 0
	s_nop 0
	s_nop 0
	s_nop 0
	s_nop 0
	s_nop 0
	s_nop 0
	s_nop 0
	s_nop 0
	s_nop 0
	s_nop 0
	s_nop 0
	s_nop 0
	s_nop 0
	s_nop 0
	s_nop 0
	s_nop 0
	s_nop 0
	s_nop 0
	s_nop 0
	s_nop 0
	s_nop 0
	s_nop 0
